# attention tiles kt>=1: exp2 of first key half against the running max in the shadow of the second half QK MFMAs (rescaled by alpha when the max grows), second half exp2 under first half PV MFMAs, V^T
# speedup vs baseline: 1.0053x; 1.0053x over previous
; #define LAS __attribute__((address_space(3)))
; __device__ __forceinline__ void attn_unit(const bf16* QB, const bf16* KN, const bf16* KR, const bf16* VT, bf16* YC, LAS unsigned char* lds, int b, int h, int u, int tid, int lane, int wave) {
;     ...
;         LAS unsigned char* st = lds + (kt & 1) * AT_STAGE;
;         if (kt < nt_wave) {
;             f32x16 sa[2];
; #pragma unroll
;             for (int mt = 0; mt < 2; ++mt) {
; #pragma unroll
;                 for (int i = 0; i < 16; ++i) sa[mt][i] = 0.f;
; #pragma unroll
;                 for (int ks = 0; ks < 12; ++ks) { const bf16x8 af = *(const LAS bf16x8*)(st + (32 * mt + r32) * AT_KSTR + 32 * ks + 16 * hi);
;                     sa[mt] = __builtin_amdgcn_mfma_f32_32x32x16_bf16(af, qf[ks], sa[mt], 0, 0, 0); }
;             }
;             float mx = sa[0][0];
; #pragma unroll
;             for (int i = 1; i < 16; ++i) mx = fmaxf(mx, sa[0][i]);
; #pragma unroll
;             for (int i = 0; i < 16; ++i) mx = fmaxf(mx, sa[1][i]);
;             mx = fmaxf(mx, __shfl_xor(mx, 32));
;             const bool grow = __builtin_amdgcn_ballot_w64(mx - m_run > 8.0f) != 0ull;
;             const float m_new = grow ? fmaxf(m_run, mx) : m_run; const float alpha = grow ? __builtin_amdgcn_exp2f(m_run - m_new) : 1.0f; m_run = m_new;
;             float ls = 0.f;
; #pragma unroll
;             for (int mt = 0; mt < 2; ++mt)
; #pragma unroll
;                 for (int i = 0; i < 16; ++i) { const float p = __builtin_amdgcn_exp2f(sa[mt][i] - m_new); sa[mt][i] = p; ls += p; }
.LBB0_1470:
	s_add_i32 s6, s4, 1
	s_bitcmp1_b32 s6, 0
	s_cselect_b32 s5, 0xac00, 0
	s_add_i32 s28, s5, 0
	s_cmp_gt_i32 s4, s0
	s_cbranch_scc1 .Lattn_stage_only
	s_cmp_eq_u32 s6, 1
	s_cbranch_scc1 .Lattn_first
	s_bitcmp1_b32 s4, 0
	s_cselect_b32 s4, 0xac00, 0
	v_add_u32_e32 v208, s4, v199
	v_add_u32_e32 v72, v208, v194
	v_add_u32_e32 v230, v208, v195
	ds_read_b128 v[210:213], v72
	ds_read_b128 v[214:217], v72 offset:32
	ds_read_b128 v[218:221], v72 offset:64
	ds_read_b128 v[222:225], v72 offset:96
	s_waitcnt lgkmcnt(3)
	v_mfma_f32_32x32x16_bf16 v[80:95], v[210:213], v[140:143], 0
	ds_read_b128 v[226:229], v72 offset:128
	v_add_u32_e32 v64, s28, v170
	s_waitcnt vmcnt(4)
	ds_write_b128 v64, v[148:151]
	s_waitcnt lgkmcnt(4)
	v_mfma_f32_32x32x16_bf16 v[80:95], v[214:217], v[136:139], v[80:95]
	ds_read_b128 v[210:213], v72 offset:160
	v_add_u32_e32 v64, s28, v174
	s_waitcnt vmcnt(3)
	ds_write_b128 v64, v[144:147] offset:25600
	s_waitcnt lgkmcnt(5)
	v_mfma_f32_32x32x16_bf16 v[80:95], v[218:221], v[132:135], v[80:95]
	ds_read_b128 v[214:217], v72 offset:192
	v_add_u32_e32 v64, s28, v172
	s_waitcnt vmcnt(2)
	ds_write_b128 v64, v[156:159]
	s_waitcnt lgkmcnt(6)
	v_mfma_f32_32x32x16_bf16 v[80:95], v[222:225], v[128:131], v[80:95]
	ds_read_b128 v[218:221], v72 offset:224
	v_add_u32_e32 v64, s28, v176
	s_waitcnt vmcnt(1)
	ds_write_b128 v64, v[152:155] offset:25600
	s_waitcnt lgkmcnt(7)
	v_mfma_f32_32x32x16_bf16 v[80:95], v[226:229], v[124:127], v[80:95]
	ds_read_b128 v[222:225], v72 offset:256
	v_add_u32_e32 v64, s28, v192
	s_waitcnt vmcnt(0)
	ds_write_b128 v64, v[160:163] offset:256
	s_waitcnt lgkmcnt(7)
	v_mfma_f32_32x32x16_bf16 v[80:95], v[210:213], v[120:123], v[80:95]
	ds_read_b128 v[226:229], v72 offset:288
	v_lshl_add_u64 v[64:65], v[168:169], 1, s[62:63]
	global_load_dwordx4 v[148:151], v[64:65], off
	s_waitcnt lgkmcnt(6)
	v_mfma_f32_32x32x16_bf16 v[80:95], v[214:217], v[116:119], v[80:95]
	ds_read_b128 v[210:213], v72 offset:320
	v_add_u32_e32 v66, v188, v207
	v_mov_b32_e32 v67, v169
	v_lshl_add_u64 v[66:67], v[66:67], 1, s[48:49]
	global_load_dwordx4 v[144:147], v[66:67], off
	s_waitcnt lgkmcnt(5)
	v_mfma_f32_32x32x16_bf16 v[80:95], v[218:221], v[112:115], v[80:95]
	ds_read_b128 v[214:217], v72 offset:352
	v_mov_b32_e32 v185, v169
	v_lshl_add_u64 v[64:65], v[184:185], 1, s[62:63]
	global_load_dwordx4 v[156:159], v[64:65], off
	s_waitcnt lgkmcnt(4)
	v_mfma_f32_32x32x16_bf16 v[80:95], v[222:225], v[108:111], v[80:95]
	ds_read_b128 v[218:221], v230
	v_add_u32_e32 v66, v188, v206
	v_mov_b32_e32 v67, v169
	v_lshl_add_u64 v[66:67], v[66:67], 1, s[48:49]
	global_load_dwordx4 v[152:155], v[66:67], off
	s_waitcnt lgkmcnt(3)
	v_mfma_f32_32x32x16_bf16 v[80:95], v[226:229], v[104:107], v[80:95]
	ds_read_b128 v[222:225], v230 offset:32
	v_add_u32_e32 v64, v188, v181
	v_mov_b32_e32 v65, v169
	v_lshl_add_u64 v[64:65], v[64:65], 1, s[54:55]
	global_load_dwordx4 v[160:163], v[64:65], off
	s_waitcnt lgkmcnt(3)
	v_mfma_f32_32x32x16_bf16 v[80:95], v[210:213], v[100:103], v[80:95]
	ds_read_b128 v[226:229], v230 offset:64
	s_waitcnt lgkmcnt(3)
	v_mfma_f32_32x32x16_bf16 v[80:95], v[214:217], v[96:99], v[80:95]
	ds_read_b128 v[210:213], v230 offset:96
	s_waitcnt lgkmcnt(3)
	v_mfma_f32_32x32x16_bf16 v[64:79], v[218:221], v[140:143], 0
	ds_read_b128 v[214:217], v230 offset:128
	s_waitcnt lgkmcnt(3)
	v_mfma_f32_32x32x16_bf16 v[64:79], v[222:225], v[136:139], v[64:79]
	ds_read_b128 v[218:221], v230 offset:160
	s_waitcnt lgkmcnt(3)
	v_mfma_f32_32x32x16_bf16 v[64:79], v[226:229], v[132:135], v[64:79]
	ds_read_b128 v[222:225], v230 offset:192
	s_waitcnt lgkmcnt(3)
	v_mfma_f32_32x32x16_bf16 v[64:79], v[210:213], v[128:131], v[64:79]
	ds_read_b128 v[226:229], v230 offset:224
	v_max_f32_e32 v209, v80, v81
	v_max3_f32 v209, v209, v82, v83
	s_waitcnt lgkmcnt(3)
	v_mfma_f32_32x32x16_bf16 v[64:79], v[214:217], v[124:127], v[64:79]
	ds_read_b128 v[210:213], v230 offset:256
	v_max3_f32 v209, v209, v84, v85
	v_max3_f32 v209, v209, v86, v87
	s_waitcnt lgkmcnt(3)
	v_mfma_f32_32x32x16_bf16 v[64:79], v[218:221], v[120:123], v[64:79]
	ds_read_b128 v[214:217], v230 offset:288
	v_max3_f32 v209, v209, v88, v89
	v_max3_f32 v209, v209, v90, v91
	s_waitcnt lgkmcnt(3)
	v_mfma_f32_32x32x16_bf16 v[64:79], v[222:225], v[116:119], v[64:79]
	ds_read_b128 v[218:221], v230 offset:320
	v_max3_f32 v209, v209, v92, v93
	v_max3_f32 v209, v209, v94, v95
	s_waitcnt lgkmcnt(3)
	v_mfma_f32_32x32x16_bf16 v[64:79], v[226:229], v[112:115], v[64:79]
	ds_read_b128 v[222:225], v230 offset:352
	v_add_u32_e32 v226, v208, v196
	v_add_u32_e32 v227, v208, v197
	v_add_u32_e32 v228, v208, v198
	v_sub_f32_e32 v80, v80, v186
	v_exp_f32_e32 v80, v80
	s_waitcnt lgkmcnt(3)
	v_mfma_f32_32x32x16_bf16 v[64:79], v[210:213], v[108:111], v[64:79]
	ds_read_b128 v[210:213], v226 offset:25600
	v_sub_f32_e32 v81, v81, v186
	v_exp_f32_e32 v81, v81
	v_sub_f32_e32 v82, v82, v186
	v_exp_f32_e32 v82, v82
	s_waitcnt lgkmcnt(3)
	v_mfma_f32_32x32x16_bf16 v[64:79], v[214:217], v[104:107], v[64:79]
	ds_read_b128 v[214:217], v227 offset:25600
	v_sub_f32_e32 v83, v83, v186
	v_exp_f32_e32 v83, v83
	v_sub_f32_e32 v84, v84, v186
	v_exp_f32_e32 v84, v84
	s_waitcnt lgkmcnt(3)
	v_mfma_f32_32x32x16_bf16 v[64:79], v[218:221], v[100:103], v[64:79]
	ds_read_b128 v[218:221], v226 offset:34816
	v_sub_f32_e32 v85, v85, v186
	v_exp_f32_e32 v85, v85
	v_sub_f32_e32 v86, v86, v186
	v_exp_f32_e32 v86, v86
	s_waitcnt lgkmcnt(3)
	v_mfma_f32_32x32x16_bf16 v[64:79], v[222:225], v[96:99], v[64:79]
	ds_read_b128 v[222:225], v228 offset:25600
	v_sub_f32_e32 v87, v87, v186
	v_exp_f32_e32 v87, v87
	v_sub_f32_e32 v88, v88, v186
	v_exp_f32_e32 v88, v88
	v_sub_f32_e32 v89, v89, v186
	v_exp_f32_e32 v89, v89
	v_sub_f32_e32 v90, v90, v186
	v_exp_f32_e32 v90, v90
	v_sub_f32_e32 v91, v91, v186
	v_exp_f32_e32 v91, v91
	v_sub_f32_e32 v92, v92, v186
	v_exp_f32_e32 v92, v92
	v_sub_f32_e32 v93, v93, v186
	v_exp_f32_e32 v93, v93
	v_sub_f32_e32 v94, v94, v186
	v_exp_f32_e32 v94, v94
	v_sub_f32_e32 v95, v95, v186
	v_exp_f32_e32 v95, v95
	v_max3_f32 v185, v209, v64, v65
	v_max3_f32 v185, v185, v66, v67
	v_max3_f32 v185, v185, v68, v69
	v_max3_f32 v185, v185, v70, v71
	v_max3_f32 v185, v185, v72, v73
	v_max3_f32 v185, v185, v74, v75
	v_max3_f32 v185, v185, v76, v77
	v_max3_f32 v185, v185, v78, v79
	v_mov_b32_e32 v209, v185
	s_nop 1
	v_permlane32_swap_b32_e32 v209, v185
	s_nop 0
	v_max_f32_e32 v209, v209, v209
	v_max_f32_e32 v185, v185, v209
	v_sub_f32_e32 v209, v185, v186
	v_cmp_lt_f32_e32 vcc, s72, v209
	s_cmp_eq_u64 vcc, 0
	v_max_f32_e32 v209, v186, v186
	v_max_f32_e32 v185, v209, v185
	s_cselect_b64 s[4:5], -1, 0
	v_cndmask_b32_e64 v185, v185, v186, s[4:5]
	v_sub_f32_e32 v186, v186, v185
	v_exp_f32_e32 v186, v186
	s_and_b64 vcc, exec, s[4:5]
	s_cbranch_vccnz .Lattn_nogrow
; #define LAS __attribute__((address_space(3)))
; __device__ __forceinline__ unsigned pk2(float a, float b) { typedef __bf16 bf2_t __attribute__((ext_vector_type(2))); f32x2 v = {a, b}; return __builtin_bit_cast(unsigned, __builtin_convertvector(v, bf2_t)); }
; __device__ __forceinline__ void attn_unit(const bf16* QB, const bf16* KN, const bf16* KR, const bf16* VT, bf16* YC, LAS unsigned char* lds, int b, int h, int u, int tid, int lane, int wave) {
;     ...
;             float ls = 0.f;
; #pragma unroll
;             for (int mt = 0; mt < 2; ++mt)
; #pragma unroll
;                 for (int i = 0; i < 16; ++i) { const float p = __builtin_amdgcn_exp2f(sa[mt][i] - m_new); sa[mt][i] = p; ls += p; }
;             l_run = l_run * alpha + ls;
;             if (grow) {
; #pragma unroll
;                 for (int d = 0; d < 4; ++d)
; #pragma unroll
;                     for (int i = 0; i < 16; ++i) ot[d][i] *= alpha;
;             }
; #pragma unroll
;             for (int mt = 0; mt < 2; ++mt)
; #pragma unroll
;                 for (int s = 0; s < 2; ++s) { u32x4 w; w.x = pk2(sa[mt][8 * s + 0], sa[mt][8 * s + 1]); w.y = pk2(sa[mt][8 * s + 2], sa[mt][8 * s + 3]); w.z = pk2(sa[mt][8 * s + 4], sa[mt][8 * s + 5]); w.w = pk2(sa[mt][8 * s + 6], sa[mt][8 * s + 7]);
;                     const bf16x8 pf = __builtin_bit_cast(bf16x8, w);
; #pragma unroll
;                     for (int d = 0; d < 4; ++d) { const bf16x8 vf = *(const LAS bf16x8*)(st + AT_KB + (32 * d + r32) * AT_VSTR + 64 * mt + 32 * s + 16 * hi);
;                         ot[d] = __builtin_amdgcn_mfma_f32_32x32x16_bf16(vf, pf, ot[d], 0, 0, 0); } }
	v_pk_mul_f32 v[62:63], v[62:63], v[186:187] op_sel_hi:[1,0]
	v_pk_mul_f32 v[60:61], v[60:61], v[186:187] op_sel_hi:[1,0]
	v_pk_mul_f32 v[58:59], v[58:59], v[186:187] op_sel_hi:[1,0]
	v_pk_mul_f32 v[56:57], v[56:57], v[186:187] op_sel_hi:[1,0]
	v_pk_mul_f32 v[54:55], v[54:55], v[186:187] op_sel_hi:[1,0]
	v_pk_mul_f32 v[52:53], v[52:53], v[186:187] op_sel_hi:[1,0]
	v_pk_mul_f32 v[50:51], v[50:51], v[186:187] op_sel_hi:[1,0]
	v_pk_mul_f32 v[48:49], v[48:49], v[186:187] op_sel_hi:[1,0]
	v_pk_mul_f32 v[46:47], v[46:47], v[186:187] op_sel_hi:[1,0]
	v_pk_mul_f32 v[44:45], v[44:45], v[186:187] op_sel_hi:[1,0]
	v_pk_mul_f32 v[42:43], v[42:43], v[186:187] op_sel_hi:[1,0]
	v_pk_mul_f32 v[40:41], v[40:41], v[186:187] op_sel_hi:[1,0]
	v_pk_mul_f32 v[38:39], v[38:39], v[186:187] op_sel_hi:[1,0]
	v_pk_mul_f32 v[36:37], v[36:37], v[186:187] op_sel_hi:[1,0]
	v_pk_mul_f32 v[34:35], v[34:35], v[186:187] op_sel_hi:[1,0]
	v_pk_mul_f32 v[32:33], v[32:33], v[186:187] op_sel_hi:[1,0]
	v_pk_mul_f32 v[30:31], v[30:31], v[186:187] op_sel_hi:[1,0]
	v_pk_mul_f32 v[28:29], v[28:29], v[186:187] op_sel_hi:[1,0]
	v_pk_mul_f32 v[26:27], v[26:27], v[186:187] op_sel_hi:[1,0]
	v_pk_mul_f32 v[24:25], v[24:25], v[186:187] op_sel_hi:[1,0]
	v_pk_mul_f32 v[22:23], v[22:23], v[186:187] op_sel_hi:[1,0]
	v_pk_mul_f32 v[20:21], v[20:21], v[186:187] op_sel_hi:[1,0]
	v_pk_mul_f32 v[18:19], v[18:19], v[186:187] op_sel_hi:[1,0]
	v_pk_mul_f32 v[16:17], v[16:17], v[186:187] op_sel_hi:[1,0]
	v_pk_mul_f32 v[14:15], v[14:15], v[186:187] op_sel_hi:[1,0]
	v_pk_mul_f32 v[12:13], v[12:13], v[186:187] op_sel_hi:[1,0]
	v_pk_mul_f32 v[10:11], v[10:11], v[186:187] op_sel_hi:[1,0]
	v_pk_mul_f32 v[8:9], v[8:9], v[186:187] op_sel_hi:[1,0]
	v_pk_mul_f32 v[6:7], v[6:7], v[186:187] op_sel_hi:[1,0]
	v_pk_mul_f32 v[4:5], v[4:5], v[186:187] op_sel_hi:[1,0]
	v_pk_mul_f32 v[2:3], v[2:3], v[186:187] op_sel_hi:[1,0]
	v_pk_mul_f32 v[0:1], v[0:1], v[186:187] op_sel_hi:[1,0]
	v_pk_mul_f32 v[80:81], v[80:81], v[186:187] op_sel_hi:[1,0]
	v_pk_mul_f32 v[82:83], v[82:83], v[186:187] op_sel_hi:[1,0]
	v_pk_mul_f32 v[84:85], v[84:85], v[186:187] op_sel_hi:[1,0]
	v_pk_mul_f32 v[86:87], v[86:87], v[186:187] op_sel_hi:[1,0]
	v_pk_mul_f32 v[88:89], v[88:89], v[186:187] op_sel_hi:[1,0]
	v_pk_mul_f32 v[90:91], v[90:91], v[186:187] op_sel_hi:[1,0]
	v_pk_mul_f32 v[92:93], v[92:93], v[186:187] op_sel_hi:[1,0]
	v_pk_mul_f32 v[94:95], v[94:95], v[186:187] op_sel_hi:[1,0]
.Lattn_nogrow:
	v_add_f32_e32 v208, v80, v81
	v_add_f32_e32 v209, v82, v83
	v_add_f32_e32 v208, v208, v84
	v_add_f32_e32 v209, v209, v86
	v_add_f32_e32 v208, v208, v85
	v_add_f32_e32 v209, v209, v87
	v_add_f32_e32 v208, v208, v88
	v_add_f32_e32 v209, v209, v90
	v_add_f32_e32 v208, v208, v89
	v_add_f32_e32 v209, v209, v91
	v_add_f32_e32 v208, v208, v92
	v_add_f32_e32 v209, v209, v94
	v_add_f32_e32 v208, v208, v93
	v_add_f32_e32 v209, v209, v95
	v_cvt_pk_bf16_f32 v80, v80, v81
	v_cvt_pk_bf16_f32 v81, v82, v83
	v_cvt_pk_bf16_f32 v82, v84, v85
	v_cvt_pk_bf16_f32 v83, v86, v87
	v_cvt_pk_bf16_f32 v88, v88, v89
	v_cvt_pk_bf16_f32 v89, v90, v91
	v_cvt_pk_bf16_f32 v90, v92, v93
	v_cvt_pk_bf16_f32 v91, v94, v95
	ds_read_b128 v[84:87], v226 offset:25632
	ds_read_b128 v[92:95], v227 offset:25632
	s_waitcnt lgkmcnt(5)
	v_mfma_f32_32x32x16_bf16 v[48:63], v[210:213], v[80:83], v[48:63]
	v_sub_f32_e32 v64, v64, v185
	v_exp_f32_e32 v64, v64
	v_sub_f32_e32 v65, v65, v185
	v_exp_f32_e32 v65, v65
	s_waitcnt lgkmcnt(4)
	v_mfma_f32_32x32x16_bf16 v[32:47], v[214:217], v[80:83], v[32:47]
	ds_read_b128 v[210:213], v226 offset:34848
	v_sub_f32_e32 v66, v66, v185
	v_exp_f32_e32 v66, v66
	v_sub_f32_e32 v67, v67, v185
	v_exp_f32_e32 v67, v67
	s_waitcnt lgkmcnt(4)
	v_mfma_f32_32x32x16_bf16 v[16:31], v[218:221], v[80:83], v[16:31]
	ds_read_b128 v[214:217], v228 offset:25632
	v_sub_f32_e32 v68, v68, v185
	v_exp_f32_e32 v68, v68
	v_sub_f32_e32 v69, v69, v185
	v_exp_f32_e32 v69, v69
	s_waitcnt lgkmcnt(4)
	v_mfma_f32_32x32x16_bf16 v[0:15], v[222:225], v[80:83], v[0:15]
	ds_read_b128 v[218:221], v226 offset:25664
	v_sub_f32_e32 v70, v70, v185
	v_exp_f32_e32 v70, v70
	v_sub_f32_e32 v71, v71, v185
	v_exp_f32_e32 v71, v71
	s_waitcnt lgkmcnt(4)
	v_mfma_f32_32x32x16_bf16 v[48:63], v[84:87], v[88:91], v[48:63]
	ds_read_b128 v[222:225], v227 offset:25664
	v_sub_f32_e32 v72, v72, v185
	v_exp_f32_e32 v72, v72
	v_sub_f32_e32 v73, v73, v185
	v_exp_f32_e32 v73, v73
	s_waitcnt lgkmcnt(4)
	v_mfma_f32_32x32x16_bf16 v[32:47], v[92:95], v[88:91], v[32:47]
	v_sub_f32_e32 v74, v74, v185
	v_exp_f32_e32 v74, v74
	v_sub_f32_e32 v75, v75, v185
	v_exp_f32_e32 v75, v75
	s_waitcnt lgkmcnt(3)
	v_mfma_f32_32x32x16_bf16 v[16:31], v[210:213], v[88:91], v[16:31]
	v_sub_f32_e32 v76, v76, v185
	v_exp_f32_e32 v76, v76
	v_sub_f32_e32 v77, v77, v185
	v_exp_f32_e32 v77, v77
	s_waitcnt lgkmcnt(2)
	v_mfma_f32_32x32x16_bf16 v[0:15], v[214:217], v[88:91], v[0:15]
	ds_read_b128 v[210:213], v226 offset:34880
	v_sub_f32_e32 v78, v78, v185
	v_exp_f32_e32 v78, v78
	v_sub_f32_e32 v79, v79, v185
	v_exp_f32_e32 v79, v79
	s_nop 0
	v_cvt_pk_bf16_f32 v84, v64, v65
	v_cvt_pk_bf16_f32 v85, v66, v67
	v_cvt_pk_bf16_f32 v86, v68, v69
	v_cvt_pk_bf16_f32 v87, v70, v71
	v_cvt_pk_bf16_f32 v92, v72, v73
	v_cvt_pk_bf16_f32 v93, v74, v75
	v_cvt_pk_bf16_f32 v94, v76, v77
	v_cvt_pk_bf16_f32 v95, v78, v79
	s_waitcnt lgkmcnt(2)
	v_mfma_f32_32x32x16_bf16 v[48:63], v[218:221], v[84:87], v[48:63]
	ds_read_b128 v[214:217], v228 offset:25664
	v_add_f32_e32 v208, v208, v64
	v_add_f32_e32 v209, v209, v66
	v_add_f32_e32 v208, v208, v65
	s_waitcnt lgkmcnt(2)
	v_mfma_f32_32x32x16_bf16 v[32:47], v[222:225], v[84:87], v[32:47]
	ds_read_b128 v[218:221], v226 offset:25696
	v_add_f32_e32 v209, v209, v67
	v_add_f32_e32 v208, v208, v68
	v_add_f32_e32 v209, v209, v70
	s_waitcnt lgkmcnt(2)
	v_mfma_f32_32x32x16_bf16 v[16:31], v[210:213], v[84:87], v[16:31]
	ds_read_b128 v[222:225], v227 offset:25696
	v_add_f32_e32 v208, v208, v69
	v_add_f32_e32 v209, v209, v71
	v_add_f32_e32 v208, v208, v72
	s_waitcnt lgkmcnt(2)
	v_mfma_f32_32x32x16_bf16 v[0:15], v[214:217], v[84:87], v[0:15]
	ds_read_b128 v[210:213], v226 offset:34912
	v_add_f32_e32 v209, v209, v74
	v_add_f32_e32 v208, v208, v73
	v_add_f32_e32 v209, v209, v75
	s_waitcnt lgkmcnt(2)
	v_mfma_f32_32x32x16_bf16 v[48:63], v[218:221], v[92:95], v[48:63]
	ds_read_b128 v[214:217], v228 offset:25696
	v_add_f32_e32 v208, v208, v76
	v_add_f32_e32 v209, v209, v78
	v_add_f32_e32 v208, v208, v77
	v_add_f32_e32 v209, v209, v79
	s_waitcnt lgkmcnt(2)
	v_mfma_f32_32x32x16_bf16 v[32:47], v[222:225], v[92:95], v[32:47]
	v_cndmask_b32_e64 v229, v186, 1.0, s[4:5]
	v_add_f32_e32 v208, v208, v209
	s_waitcnt lgkmcnt(1)
	v_mfma_f32_32x32x16_bf16 v[16:31], v[210:213], v[92:95], v[16:31]
	v_fmac_f32_e32 v208, v179, v229
	s_waitcnt lgkmcnt(0)
	v_mfma_f32_32x32x16_bf16 v[0:15], v[214:217], v[92:95], v[0:15]
	v_mov_b32_e32 v179, v208
	s_branch .LBB0_1475
; #define LAS __attribute__((address_space(3)))
; __device__ __forceinline__ void attn_unit(const bf16* QB, const bf16* KN, const bf16* KR, const bf16* VT, bf16* YC, LAS unsigned char* lds, int b, int h, int u, int tid, int lane, int wave) {
;     ...
;         LAS unsigned char* st = lds + (kt & 1) * AT_STAGE;
;         if (kt < nt_wave) {
;             f32x16 sa[2];
; #pragma unroll
;             for (int mt = 0; mt < 2; ++mt) {
; #pragma unroll
;                 for (int i = 0; i < 16; ++i) sa[mt][i] = 0.f;
; #pragma unroll
;                 for (int ks = 0; ks < 12; ++ks) { const bf16x8 af = *(const LAS bf16x8*)(st + (32 * mt + r32) * AT_KSTR + 32 * ks + 16 * hi);
;                     sa[mt] = __builtin_amdgcn_mfma_f32_32x32x16_bf16(af, qf[ks], sa[mt], 0, 0, 0); }
;             }
;             float mx = sa[0][0];
; #pragma unroll
;             for (int i = 1; i < 16; ++i) mx = fmaxf(mx, sa[0][i]);
; #pragma unroll
;             for (int i = 0; i < 16; ++i) mx = fmaxf(mx, sa[1][i]);
;             mx = fmaxf(mx, __shfl_xor(mx, 32));
;             const bool grow = __builtin_amdgcn_ballot_w64(mx - m_run > 8.0f) != 0ull;
;             const float m_new = grow ? fmaxf(m_run, mx) : m_run; const float alpha = grow ? __builtin_amdgcn_exp2f(m_run - m_new) : 1.0f; m_run = m_new;
.Lattn_first:
	s_bitcmp1_b32 s4, 0
	s_cselect_b32 s4, 0xac00, 0
	v_add_u32_e32 v208, s4, v199
	v_add_u32_e32 v72, v208, v194
	v_add_u32_e32 v230, v208, v195
	ds_read_b128 v[210:213], v72
	ds_read_b128 v[214:217], v72 offset:32
	ds_read_b128 v[218:221], v72 offset:64
	ds_read_b128 v[222:225], v72 offset:96
	s_waitcnt lgkmcnt(3)
	v_mfma_f32_32x32x16_bf16 v[80:95], v[210:213], v[140:143], 0
	ds_read_b128 v[226:229], v72 offset:128
	v_add_u32_e32 v64, s28, v170
	s_waitcnt vmcnt(4)
	ds_write_b128 v64, v[148:151]
	s_waitcnt lgkmcnt(4)
	v_mfma_f32_32x32x16_bf16 v[80:95], v[214:217], v[136:139], v[80:95]
	ds_read_b128 v[210:213], v72 offset:160
	v_add_u32_e32 v64, s28, v174
	s_waitcnt vmcnt(3)
	ds_write_b128 v64, v[144:147] offset:25600
	s_waitcnt lgkmcnt(5)
	v_mfma_f32_32x32x16_bf16 v[80:95], v[218:221], v[132:135], v[80:95]
	ds_read_b128 v[214:217], v72 offset:192
	v_add_u32_e32 v64, s28, v172
	s_waitcnt vmcnt(2)
	ds_write_b128 v64, v[156:159]
	s_waitcnt lgkmcnt(6)
	v_mfma_f32_32x32x16_bf16 v[80:95], v[222:225], v[128:131], v[80:95]
	ds_read_b128 v[218:221], v72 offset:224
	v_add_u32_e32 v64, s28, v176
	s_waitcnt vmcnt(1)
	ds_write_b128 v64, v[152:155] offset:25600
	s_waitcnt lgkmcnt(7)
	v_mfma_f32_32x32x16_bf16 v[80:95], v[226:229], v[124:127], v[80:95]
	ds_read_b128 v[222:225], v72 offset:256
	v_add_u32_e32 v64, s28, v192
	s_waitcnt vmcnt(0)
	ds_write_b128 v64, v[160:163] offset:256
	s_waitcnt lgkmcnt(7)
	v_mfma_f32_32x32x16_bf16 v[80:95], v[210:213], v[120:123], v[80:95]
	ds_read_b128 v[226:229], v72 offset:288
	v_lshl_add_u64 v[64:65], v[168:169], 1, s[62:63]
	global_load_dwordx4 v[148:151], v[64:65], off
	s_waitcnt lgkmcnt(6)
	v_mfma_f32_32x32x16_bf16 v[80:95], v[214:217], v[116:119], v[80:95]
	ds_read_b128 v[210:213], v72 offset:320
	v_add_u32_e32 v66, v188, v207
	v_mov_b32_e32 v67, v169
	v_lshl_add_u64 v[66:67], v[66:67], 1, s[48:49]
	global_load_dwordx4 v[144:147], v[66:67], off
	s_waitcnt lgkmcnt(5)
	v_mfma_f32_32x32x16_bf16 v[80:95], v[218:221], v[112:115], v[80:95]
	ds_read_b128 v[214:217], v72 offset:352
	v_mov_b32_e32 v185, v169
	v_lshl_add_u64 v[64:65], v[184:185], 1, s[62:63]
	global_load_dwordx4 v[156:159], v[64:65], off
	s_waitcnt lgkmcnt(4)
	v_mfma_f32_32x32x16_bf16 v[80:95], v[222:225], v[108:111], v[80:95]
	ds_read_b128 v[218:221], v230
	v_add_u32_e32 v66, v188, v206
	v_mov_b32_e32 v67, v169
	v_lshl_add_u64 v[66:67], v[66:67], 1, s[48:49]
	global_load_dwordx4 v[152:155], v[66:67], off
	s_waitcnt lgkmcnt(3)
	v_mfma_f32_32x32x16_bf16 v[80:95], v[226:229], v[104:107], v[80:95]
	ds_read_b128 v[222:225], v230 offset:32
	v_add_u32_e32 v64, v188, v181
	v_mov_b32_e32 v65, v169
	v_lshl_add_u64 v[64:65], v[64:65], 1, s[54:55]
	global_load_dwordx4 v[160:163], v[64:65], off
	s_waitcnt lgkmcnt(3)
	v_mfma_f32_32x32x16_bf16 v[80:95], v[210:213], v[100:103], v[80:95]
	ds_read_b128 v[226:229], v230 offset:64
	s_waitcnt lgkmcnt(3)
	v_mfma_f32_32x32x16_bf16 v[80:95], v[214:217], v[96:99], v[80:95]
	ds_read_b128 v[210:213], v230 offset:96
	s_waitcnt lgkmcnt(3)
	v_mfma_f32_32x32x16_bf16 v[64:79], v[218:221], v[140:143], 0
	ds_read_b128 v[214:217], v230 offset:128
	s_waitcnt lgkmcnt(3)
	v_mfma_f32_32x32x16_bf16 v[64:79], v[222:225], v[136:139], v[64:79]
	ds_read_b128 v[218:221], v230 offset:160
	s_waitcnt lgkmcnt(3)
	v_mfma_f32_32x32x16_bf16 v[64:79], v[226:229], v[132:135], v[64:79]
	ds_read_b128 v[222:225], v230 offset:192
	s_waitcnt lgkmcnt(3)
	v_mfma_f32_32x32x16_bf16 v[64:79], v[210:213], v[128:131], v[64:79]
	ds_read_b128 v[226:229], v230 offset:224
	s_waitcnt lgkmcnt(3)
	v_mfma_f32_32x32x16_bf16 v[64:79], v[214:217], v[124:127], v[64:79]
	ds_read_b128 v[210:213], v230 offset:256
	v_max_f32_e32 v209, v80, v81
	v_max3_f32 v209, v209, v82, v83
	s_waitcnt lgkmcnt(3)
	v_mfma_f32_32x32x16_bf16 v[64:79], v[218:221], v[120:123], v[64:79]
	ds_read_b128 v[214:217], v230 offset:288
	v_max3_f32 v209, v209, v84, v85
	s_waitcnt lgkmcnt(3)
	v_mfma_f32_32x32x16_bf16 v[64:79], v[222:225], v[116:119], v[64:79]
	ds_read_b128 v[218:221], v230 offset:320
	v_max3_f32 v209, v209, v86, v87
	s_waitcnt lgkmcnt(3)
	v_mfma_f32_32x32x16_bf16 v[64:79], v[226:229], v[112:115], v[64:79]
	ds_read_b128 v[222:225], v230 offset:352
	v_max3_f32 v209, v209, v88, v89
	s_waitcnt lgkmcnt(3)
	v_mfma_f32_32x32x16_bf16 v[64:79], v[210:213], v[108:111], v[64:79]
	v_max3_f32 v209, v209, v90, v91
	s_waitcnt lgkmcnt(2)
	v_mfma_f32_32x32x16_bf16 v[64:79], v[214:217], v[104:107], v[64:79]
	v_max3_f32 v209, v209, v92, v93
	s_waitcnt lgkmcnt(1)
	v_mfma_f32_32x32x16_bf16 v[64:79], v[218:221], v[100:103], v[64:79]
	v_max3_f32 v209, v209, v94, v95
	s_waitcnt lgkmcnt(0)
	v_mfma_f32_32x32x16_bf16 v[64:79], v[222:225], v[96:99], v[64:79]
	s_nop 7
	s_nop 3
	v_max3_f32 v185, v209, v64, v65
	v_max3_f32 v185, v185, v66, v67
	v_max3_f32 v185, v185, v68, v69
	v_max3_f32 v185, v185, v70, v71
	v_max3_f32 v185, v185, v72, v73
	v_max3_f32 v185, v185, v74, v75
	v_max3_f32 v185, v185, v76, v77
	v_max3_f32 v185, v185, v78, v79
	v_mov_b32_e32 v209, v185
	s_nop 1
	v_permlane32_swap_b32_e32 v209, v185
	s_waitcnt lgkmcnt(0)
	v_max_f32_e32 v209, v209, v209
	v_max_f32_e32 v185, v185, v209
	v_sub_f32_e32 v209, v185, v186
	v_cmp_lt_f32_e32 vcc, s72, v209
	s_cmp_eq_u64 vcc, 0
	v_max_f32_e32 v209, v186, v186
	v_max_f32_e32 v185, v209, v185
	s_cselect_b64 s[4:5], -1, 0
	v_cndmask_b32_e64 v185, v185, v186, s[4:5]
	v_sub_f32_e32 v186, v186, v185
	v_exp_f32_e32 v186, v186
	s_and_b64 vcc, exec, s[4:5]
	s_cbranch_vccnz .LBB0_1473
; __device__ __forceinline__ void attn_unit(const bf16* QB, const bf16* KN, const bf16* KR, const bf16* VT, bf16* YC, LAS unsigned char* lds, int b, int h, int u, int tid, int lane, int wave) {
;     ...
;             if (grow) {
; #pragma unroll
;                 for (int d = 0; d < 4; ++d)
; #pragma unroll
;                     for (int i = 0; i < 16; ++i) ot[d][i] *= alpha;
;             }
	v_pk_mul_f32 v[62:63], v[62:63], v[186:187] op_sel_hi:[1,0]
	v_pk_mul_f32 v[60:61], v[60:61], v[186:187] op_sel_hi:[1,0]
	v_pk_mul_f32 v[58:59], v[58:59], v[186:187] op_sel_hi:[1,0]
	v_pk_mul_f32 v[56:57], v[56:57], v[186:187] op_sel_hi:[1,0]
	v_pk_mul_f32 v[54:55], v[54:55], v[186:187] op_sel_hi:[1,0]
	v_pk_mul_f32 v[52:53], v[52:53], v[186:187] op_sel_hi:[1,0]
	v_pk_mul_f32 v[50:51], v[50:51], v[186:187] op_sel_hi:[1,0]
	v_pk_mul_f32 v[48:49], v[48:49], v[186:187] op_sel_hi:[1,0]
	v_pk_mul_f32 v[46:47], v[46:47], v[186:187] op_sel_hi:[1,0]
	v_pk_mul_f32 v[44:45], v[44:45], v[186:187] op_sel_hi:[1,0]
	v_pk_mul_f32 v[42:43], v[42:43], v[186:187] op_sel_hi:[1,0]
	v_pk_mul_f32 v[40:41], v[40:41], v[186:187] op_sel_hi:[1,0]
	v_pk_mul_f32 v[38:39], v[38:39], v[186:187] op_sel_hi:[1,0]
	v_pk_mul_f32 v[36:37], v[36:37], v[186:187] op_sel_hi:[1,0]
	v_pk_mul_f32 v[34:35], v[34:35], v[186:187] op_sel_hi:[1,0]
	v_pk_mul_f32 v[32:33], v[32:33], v[186:187] op_sel_hi:[1,0]
	v_pk_mul_f32 v[30:31], v[30:31], v[186:187] op_sel_hi:[1,0]
	v_pk_mul_f32 v[28:29], v[28:29], v[186:187] op_sel_hi:[1,0]
	v_pk_mul_f32 v[26:27], v[26:27], v[186:187] op_sel_hi:[1,0]
	v_pk_mul_f32 v[24:25], v[24:25], v[186:187] op_sel_hi:[1,0]
	v_pk_mul_f32 v[22:23], v[22:23], v[186:187] op_sel_hi:[1,0]
	v_pk_mul_f32 v[20:21], v[20:21], v[186:187] op_sel_hi:[1,0]
	v_pk_mul_f32 v[18:19], v[18:19], v[186:187] op_sel_hi:[1,0]
	v_pk_mul_f32 v[16:17], v[16:17], v[186:187] op_sel_hi:[1,0]
	v_pk_mul_f32 v[14:15], v[14:15], v[186:187] op_sel_hi:[1,0]
	v_pk_mul_f32 v[12:13], v[12:13], v[186:187] op_sel_hi:[1,0]
	v_pk_mul_f32 v[10:11], v[10:11], v[186:187] op_sel_hi:[1,0]
	v_pk_mul_f32 v[8:9], v[8:9], v[186:187] op_sel_hi:[1,0]
	v_pk_mul_f32 v[6:7], v[6:7], v[186:187] op_sel_hi:[1,0]
	v_pk_mul_f32 v[4:5], v[4:5], v[186:187] op_sel_hi:[1,0]
	v_pk_mul_f32 v[2:3], v[2:3], v[186:187] op_sel_hi:[1,0]
	v_pk_mul_f32 v[0:1], v[0:1], v[186:187] op_sel_hi:[1,0]
